# sgu phase: the three serialized kk MFMA sections (reads into one register quad, lgkmcnt(0) before every MFMA) rewritten with the 16 transposed LDS reads in flight in distinct registers and counted wai
# speedup vs baseline: 1.0080x; 1.0080x over previous
; #define LAS __attribute__((address_space(3)))
; __device__ __forceinline__ void sgu_phase(CArgs* a, LAS unsigned char* lds, int G, int tid, int wave, int lane) {
;     ...
;             for (int kk = 0; kk < 4; ++kk) if (kk < nkk) { const bf16x8 xf = xfr[kk];
; #pragma unroll
;                 for (int cbk = 0; cbk < 8; ++cbk) {
;                     const s16x4 p0 = __builtin_amdgcn_ds_read_tr16_b64_v4i16((LAS s16x4*)(VN + troff + (32 * kk) * VS + 32 * cbk));
;                     const s16x4 p1 = __builtin_amdgcn_ds_read_tr16_b64_v4i16((LAS s16x4*)(VN + troff + (32 * kk + 4) * VS + 32 * cbk));
;                     const bf16x8 yf = __builtin_shufflevector(p0, p1, 0, 1, 2, 3, 4, 5, 6, 7);
;                     acc[cbk] = __builtin_amdgcn_mfma_f32_16x16x32_bf16(yf, xf, acc[cbk], 0, 0, 0); } }
.LBB0_954:
	ds_read_b64_tr_b16 v[32:33], v60
	ds_read_b64_tr_b16 v[34:35], v60 offset:1088
	ds_read_b64_tr_b16 v[38:39], v60 offset:1120
	ds_read_b64_tr_b16 v[36:37], v60 offset:32
	ds_read_b64_tr_b16 v[40:41], v60 offset:64
	ds_read_b64_tr_b16 v[48:49], v60 offset:96
	ds_read_b64_tr_b16 v[42:43], v60 offset:1152
	ds_read_b64_tr_b16 v[50:51], v60 offset:1184
	s_waitcnt vmcnt(9) lgkmcnt(6)
	v_mfma_f32_16x16x32_bf16 v[56:59], v[32:35], v[28:31], 0
	ds_read_b64_tr_b16 v[32:33], v60 offset:128
	ds_read_b64_tr_b16 v[34:35], v60 offset:1216
	s_and_b64 vcc, exec, s[14:15]
	s_waitcnt lgkmcnt(6)
	v_mfma_f32_16x16x32_bf16 v[52:55], v[36:39], v[28:31], 0
	ds_read_b64_tr_b16 v[38:39], v60 offset:1248
	ds_read_b64_tr_b16 v[36:37], v60 offset:160
	ds_read_b64_tr_b16 v[132:133], v60 offset:192
	ds_read_b64_tr_b16 v[136:137], v60 offset:224
	ds_read_b64_tr_b16 v[134:135], v60 offset:1280
	ds_read_b64_tr_b16 v[138:139], v60 offset:1312
	s_waitcnt lgkmcnt(9)
	v_mfma_f32_16x16x32_bf16 v[44:47], v[40:43], v[28:31], 0
	s_waitcnt lgkmcnt(8)
	v_mfma_f32_16x16x32_bf16 v[40:43], v[48:51], v[28:31], 0
	s_waitcnt lgkmcnt(6)
	v_mfma_f32_16x16x32_bf16 v[48:51], v[32:35], v[28:31], 0
	s_waitcnt lgkmcnt(4)
	v_mfma_f32_16x16x32_bf16 v[36:39], v[36:39], v[28:31], 0
	s_waitcnt lgkmcnt(1)
	v_mfma_f32_16x16x32_bf16 v[32:35], v[132:135], v[28:31], 0
	s_waitcnt lgkmcnt(0)
	v_mfma_f32_16x16x32_bf16 v[28:31], v[136:139], v[28:31], 0
	s_cbranch_vccnz .LBB0_959
	ds_read_b64_tr_b16 v[208:209], v60 offset:8704
	ds_read_b64_tr_b16 v[210:211], v60 offset:9792
	ds_read_b64_tr_b16 v[212:213], v60 offset:8768
	ds_read_b64_tr_b16 v[214:215], v60 offset:9856
	ds_read_b64_tr_b16 v[216:217], v60 offset:8800
	ds_read_b64_tr_b16 v[218:219], v60 offset:9888
	ds_read_b64_tr_b16 v[220:221], v60 offset:8832
	ds_read_b64_tr_b16 v[222:223], v60 offset:9920
	ds_read_b64_tr_b16 v[224:225], v60 offset:8864
	ds_read_b64_tr_b16 v[226:227], v60 offset:9952
	ds_read_b64_tr_b16 v[230:231], v60 offset:8896
	ds_read_b64_tr_b16 v[232:233], v60 offset:9984
	s_waitcnt lgkmcnt(10)
	v_mfma_f32_16x16x32_bf16 v[56:59], v[208:211], v[0:3], v[56:59]
	ds_read_b64_tr_b16 v[234:235], v60 offset:8736
	ds_read_b64_tr_b16 v[236:237], v60 offset:9824
	s_waitcnt lgkmcnt(10)
	v_mfma_f32_16x16x32_bf16 v[44:47], v[212:215], v[0:3], v[44:47]
	ds_read_b64_tr_b16 v[238:239], v60 offset:8928
	ds_read_b64_tr_b16 v[240:241], v60 offset:10016
	s_waitcnt lgkmcnt(10)
	v_mfma_f32_16x16x32_bf16 v[40:43], v[216:219], v[0:3], v[40:43]
	s_waitcnt lgkmcnt(8)
	v_mfma_f32_16x16x32_bf16 v[48:51], v[220:223], v[0:3], v[48:51]
	s_waitcnt lgkmcnt(6)
	v_mfma_f32_16x16x32_bf16 v[36:39], v[224:227], v[0:3], v[36:39]
	s_waitcnt lgkmcnt(4)
	v_mfma_f32_16x16x32_bf16 v[32:35], v[230:233], v[0:3], v[32:35]
	s_waitcnt lgkmcnt(2)
	v_mfma_f32_16x16x32_bf16 v[52:55], v[234:237], v[0:3], v[52:55]
	s_waitcnt lgkmcnt(0)
	v_mfma_f32_16x16x32_bf16 v[28:31], v[238:241], v[0:3], v[28:31]
	s_and_b64 vcc, exec, s[12:13]
	s_cbranch_vccz .LBB0_960

; #define LAS __attribute__((address_space(3)))
; __device__ __forceinline__ void sgu_phase(CArgs* a, LAS unsigned char* lds, int G, int tid, int wave, int lane) {
;     ...
;             for (int kk = 0; kk < 4; ++kk) if (kk < nkk) { const bf16x8 xf = xfr[kk];
; #pragma unroll
;                 for (int cbk = 0; cbk < 8; ++cbk) {
;                     const s16x4 p0 = __builtin_amdgcn_ds_read_tr16_b64_v4i16((LAS s16x4*)(VN + troff + (32 * kk) * VS + 32 * cbk));
;                     const s16x4 p1 = __builtin_amdgcn_ds_read_tr16_b64_v4i16((LAS s16x4*)(VN + troff + (32 * kk + 4) * VS + 32 * cbk));
;                     const bf16x8 yf = __builtin_shufflevector(p0, p1, 0, 1, 2, 3, 4, 5, 6, 7);
;                     acc[cbk] = __builtin_amdgcn_mfma_f32_16x16x32_bf16(yf, xf, acc[cbk], 0, 0, 0); } }
.LBB0_960:
	ds_read_b64_tr_b16 v[208:209], v60 offset:17408
	ds_read_b64_tr_b16 v[210:211], v60 offset:18496
	ds_read_b64_tr_b16 v[212:213], v60 offset:17472
	ds_read_b64_tr_b16 v[214:215], v60 offset:18560
	ds_read_b64_tr_b16 v[216:217], v60 offset:17504
	ds_read_b64_tr_b16 v[218:219], v60 offset:18592
	ds_read_b64_tr_b16 v[220:221], v60 offset:17536
	ds_read_b64_tr_b16 v[222:223], v60 offset:18624
	ds_read_b64_tr_b16 v[224:225], v60 offset:17568
	ds_read_b64_tr_b16 v[226:227], v60 offset:18656
	ds_read_b64_tr_b16 v[230:231], v60 offset:17600
	ds_read_b64_tr_b16 v[232:233], v60 offset:18688
	s_waitcnt lgkmcnt(10)
	v_mfma_f32_16x16x32_bf16 v[56:59], v[208:211], v[4:7], v[56:59]
	ds_read_b64_tr_b16 v[234:235], v60 offset:17440
	ds_read_b64_tr_b16 v[236:237], v60 offset:18528
	s_waitcnt lgkmcnt(10)
	v_mfma_f32_16x16x32_bf16 v[44:47], v[212:215], v[4:7], v[44:47]
	ds_read_b64_tr_b16 v[238:239], v60 offset:17632
	ds_read_b64_tr_b16 v[240:241], v60 offset:18720
	s_waitcnt lgkmcnt(10)
	v_mfma_f32_16x16x32_bf16 v[40:43], v[216:219], v[4:7], v[40:43]
	s_waitcnt lgkmcnt(8)
	v_mfma_f32_16x16x32_bf16 v[48:51], v[220:223], v[4:7], v[48:51]
	s_waitcnt lgkmcnt(6)
	v_mfma_f32_16x16x32_bf16 v[36:39], v[224:227], v[4:7], v[36:39]
	s_waitcnt lgkmcnt(4)
	v_mfma_f32_16x16x32_bf16 v[32:35], v[230:233], v[4:7], v[32:35]
	s_waitcnt lgkmcnt(2)
	v_mfma_f32_16x16x32_bf16 v[52:55], v[234:237], v[4:7], v[52:55]
	s_waitcnt lgkmcnt(0)
	v_mfma_f32_16x16x32_bf16 v[28:31], v[238:241], v[4:7], v[28:31]
	s_and_b64 vcc, exec, s[10:11]
	s_cbranch_vccnz .LBB0_947
.LBB0_961:
	ds_read_b64_tr_b16 v[208:209], v60 offset:26112
	ds_read_b64_tr_b16 v[210:211], v60 offset:27200
	ds_read_b64_tr_b16 v[212:213], v60 offset:26176
	ds_read_b64_tr_b16 v[214:215], v60 offset:27264
	ds_read_b64_tr_b16 v[216:217], v60 offset:26208
	ds_read_b64_tr_b16 v[218:219], v60 offset:27296
	ds_read_b64_tr_b16 v[220:221], v60 offset:26240
	ds_read_b64_tr_b16 v[222:223], v60 offset:27328
	ds_read_b64_tr_b16 v[224:225], v60 offset:26272
	ds_read_b64_tr_b16 v[226:227], v60 offset:27360
	ds_read_b64_tr_b16 v[230:231], v60 offset:26304
	ds_read_b64_tr_b16 v[232:233], v60 offset:27392
	s_waitcnt lgkmcnt(10)
	v_mfma_f32_16x16x32_bf16 v[56:59], v[208:211], v[8:11], v[56:59]
	ds_read_b64_tr_b16 v[234:235], v60 offset:26144
	ds_read_b64_tr_b16 v[236:237], v60 offset:27232
	s_waitcnt lgkmcnt(10)
	v_mfma_f32_16x16x32_bf16 v[44:47], v[212:215], v[8:11], v[44:47]
	ds_read_b64_tr_b16 v[238:239], v60 offset:26336
	ds_read_b64_tr_b16 v[240:241], v60 offset:27424
	s_waitcnt lgkmcnt(10)
	v_mfma_f32_16x16x32_bf16 v[40:43], v[216:219], v[8:11], v[40:43]
	s_waitcnt lgkmcnt(8)
	v_mfma_f32_16x16x32_bf16 v[48:51], v[220:223], v[8:11], v[48:51]
	s_waitcnt lgkmcnt(6)
	v_mfma_f32_16x16x32_bf16 v[36:39], v[224:227], v[8:11], v[36:39]
	s_waitcnt lgkmcnt(4)
	v_mfma_f32_16x16x32_bf16 v[32:35], v[230:233], v[8:11], v[32:35]
	s_waitcnt lgkmcnt(2)
	v_mfma_f32_16x16x32_bf16 v[52:55], v[234:237], v[8:11], v[52:55]
	s_waitcnt lgkmcnt(0)
	v_mfma_f32_16x16x32_bf16 v[28:31], v[238:241], v[8:11], v[28:31]
	s_branch .LBB0_947
